# v19 plus deep LDS prefetch of next-tile QK fragments in NSA window/selected loops
# speedup vs baseline: 1.0038x; 1.0019x over previous
; #define LAS __attribute__((address_space(3)))
; __device__ __forceinline__ f32x16 mfma32(bf16x8 a, bf16x8 b, f32x16 c) { return __builtin_amdgcn_mfma_f32_32x32x16_bf16(a, b, c, 0, 0, 0); }
; template <int MODE> ...
;     ...
;     { const LAS unsigned char* kp = lds + NSA_KB + bufn * 16384 + lane * 16;
; #pragma unroll
;       for (int kt = 0; kt < 2; ++kt) { sn[kt] = zero16();
; #pragma unroll
;           for (int ks = 0; ks < 8; ++ks) sn[kt] = mfma32(*(const LAS bf16x8*)(kp + kt * 8192 + ks * 1024), qf[ks], sn[kt]); } }
;     if (MODE == 1) {
; #pragma unroll
;         for (int kt = 0; kt < 2; ++kt)
; #pragma unroll
;             for (int r = 0; r < 16; ++r) s[kt][r] = (s[kt][r] > -1e29f) ? __builtin_amdgcn_exp2f(s[kt][r] - m_fin) * invl : 0.f;
;         LAS float* impa = (LAS float*)(lds + NSA_IMPA) + w * 8 * 66;
;         LAS float* impb = (LAS float*)(lds + NSA_IMPB) + w * 8 * 66;
; #pragma unroll
;         for (int kt = 0; kt < 2; ++kt)
; #pragma unroll
;             for (int q = 0; q < 4; ++q) {
;                 float A_ = s[kt][4 * q] + s[kt][4 * q + 1] + s[kt][4 * q + 2] + 0.5f * s[kt][4 * q + 3], B_ = 0.5f * s[kt][4 * q + 3];
;                 A_ += __shfl_xor(A_, 1); A_ += __shfl_xor(A_, 2); B_ += __shfl_xor(B_, 1); B_ += __shfl_xor(B_, 2);
;                 const int j = 8 * (2 * idx + kt) + 2 * q + hi;
;                 if (hd == 0) { impa[tl * 66 + j] = A_; impb[tl * 66 + j + 1] = B_; }
;             }
;     } else {
;         float tm = -3.0e38f;
; #pragma unroll
;         for (int kt = 0; kt < 2; ++kt)
; #pragma unroll
;             for (int r = 0; r < 16; r += 2) tm = fmaxf(fmaxf(tm, s[kt][r]), s[kt][r + 1]);
;         tm = tm * cs + offl;
;         tm = max_xor32(tm);
;         const float mn = fmaxf(mrun, tm), al = __builtin_amdgcn_exp2f(mrun - mn); float ps = 0.f;
;         const float om = offl - mn;
; #pragma unroll
;         for (int kt = 0; kt < 2; ++kt)
; #pragma unroll
;             for (int r = 0; r < 16; ++r) { const float p = __builtin_amdgcn_exp2f(s[kt][r] * cs + om); s[kt][r] = p; ps += p; }
;         lrun = lrun * al + ps; mrun = mn;
;         if (MODE != 0) {
;             if (__builtin_amdgcn_ballot_w64(al != 1.0f)) {
; #pragma unroll
;                 for (int dt = 0; dt < 4; ++dt) O[dt] = O[dt] * al;
;             }
;         }
.LBB0_1219:
	s_lshl_b32 s7, s13, 14
	s_add_i32 s7, s7, 0
	v_lshlrev_b32_e32 v171, 4, v64
	v_add_u32_e32 v64, s7, v171
	ds_read_b128 v[218:221], v64
	ds_read_b128 v[224:227], v64 offset:1024
	ds_read_b128 v[228:231], v64 offset:2048
	ds_read_b128 v[232:235], v64 offset:3072
	ds_read_b128 v[236:239], v64 offset:4096
	ds_read_b128 v[240:243], v64 offset:5120
	ds_read_b128 v[244:247], v64 offset:6144
	ds_read_b128 v[248:251], v64 offset:7168
	ds_read_b128 v[174:177], v64 offset:8192
	ds_read_b128 v[178:181], v64 offset:9216
	ds_read_b128 v[182:185], v64 offset:10240
	ds_read_b128 v[186:189], v64 offset:11264
	s_waitcnt lgkmcnt(11)
	v_mfma_f32_32x32x16_bf16 v[0:15], v[218:221], v[154:157], 0
	s_waitcnt lgkmcnt(10)
	v_mfma_f32_32x32x16_bf16 v[0:15], v[224:227], v[130:133], v[0:15]
	ds_read_b128 v[218:221], v64 offset:12288
	ds_read_b128 v[224:227], v64 offset:13312
	s_waitcnt lgkmcnt(11)
	v_mfma_f32_32x32x16_bf16 v[0:15], v[228:231], v[134:137], v[0:15]
	s_waitcnt lgkmcnt(10)
	v_mfma_f32_32x32x16_bf16 v[0:15], v[232:235], v[138:141], v[0:15]
	ds_read_b128 v[228:231], v64 offset:14336
	ds_read_b128 v[232:235], v64 offset:15360
	s_waitcnt lgkmcnt(11)
	v_mfma_f32_32x32x16_bf16 v[0:15], v[236:239], v[142:145], v[0:15]
	s_waitcnt lgkmcnt(10)
	v_mfma_f32_32x32x16_bf16 v[0:15], v[240:243], v[146:149], v[0:15]
	s_waitcnt lgkmcnt(9)
	v_mfma_f32_32x32x16_bf16 v[0:15], v[244:247], v[150:153], v[0:15]
	s_waitcnt lgkmcnt(8)
	v_mfma_f32_32x32x16_bf16 v[0:15], v[248:251], v[158:161], v[0:15]
	s_waitcnt lgkmcnt(7)
	v_mfma_f32_32x32x16_bf16 v[16:31], v[174:177], v[154:157], 0
	s_waitcnt lgkmcnt(6)
	v_mfma_f32_32x32x16_bf16 v[16:31], v[178:181], v[130:133], v[16:31]
	s_waitcnt lgkmcnt(5)
	v_mfma_f32_32x32x16_bf16 v[16:31], v[182:185], v[134:137], v[16:31]
	s_waitcnt lgkmcnt(4)
	v_mfma_f32_32x32x16_bf16 v[16:31], v[186:189], v[138:141], v[16:31]
	v_max3_f32 v64, v32, s78, v33
	v_max3_f32 v64, v64, v34, v35
	v_max3_f32 v64, v64, v36, v37
	v_max3_f32 v64, v64, v38, v39
	v_max3_f32 v64, v64, v40, v41
	v_max3_f32 v64, v64, v42, v43
	s_waitcnt lgkmcnt(3)
	v_mfma_f32_32x32x16_bf16 v[16:31], v[218:221], v[142:145], v[16:31]
	v_max3_f32 v64, v64, v44, v45
	v_max3_f32 v64, v64, v46, v47
	v_max3_f32 v64, v64, v48, v49
	v_max3_f32 v64, v64, v50, v51
	v_max3_f32 v64, v64, v52, v53
	v_max3_f32 v64, v64, v54, v55
	v_max3_f32 v64, v64, v56, v57
	s_waitcnt lgkmcnt(2)
	v_mfma_f32_32x32x16_bf16 v[16:31], v[224:227], v[146:149], v[16:31]
	v_max3_f32 v64, v64, v58, v59
	v_max3_f32 v64, v64, v60, v61
	v_max3_f32 v64, v64, v62, v63
	v_fma_f32 v64, s6, v64, v172
	v_mov_b32_e32 v170, v64
	s_nop 1
	v_permlane32_swap_b32 v64, v170
	s_nop 1
	s_waitcnt lgkmcnt(1)
	v_mfma_f32_32x32x16_bf16 v[16:31], v[228:231], v[150:153], v[16:31]
	v_max_f32_e32 v170, v64, v170
	v_add_f32_e32 v64, 0x41000000, v169
	v_cmp_gt_f32_e32 vcc, v170, v64
	s_nop 1
	v_cndmask_b32_e32 v170, v169, v170, vcc
	v_sub_f32_e32 v64, v169, v170
	v_exp_f32_e32 v64, v64
	s_nop 0
	v_cmp_neq_f32_e32 vcc, 1.0, v64
	s_waitcnt lgkmcnt(0)
	v_mfma_f32_32x32x16_bf16 v[16:31], v[232:235], v[158:161], v[16:31]
	s_cbranch_vccz .LBB0_1221
	v_pk_mul_f32 v[128:129], v[128:129], v[64:65] op_sel_hi:[1,0]
	v_pk_mul_f32 v[126:127], v[126:127], v[64:65] op_sel_hi:[1,0]
	v_pk_mul_f32 v[124:125], v[124:125], v[64:65] op_sel_hi:[1,0]
	v_pk_mul_f32 v[122:123], v[122:123], v[64:65] op_sel_hi:[1,0]
	v_pk_mul_f32 v[120:121], v[120:121], v[64:65] op_sel_hi:[1,0]
	v_pk_mul_f32 v[118:119], v[118:119], v[64:65] op_sel_hi:[1,0]
	v_pk_mul_f32 v[116:117], v[116:117], v[64:65] op_sel_hi:[1,0]
	v_pk_mul_f32 v[114:115], v[114:115], v[64:65] op_sel_hi:[1,0]
	v_pk_mul_f32 v[112:113], v[112:113], v[64:65] op_sel_hi:[1,0]
	v_pk_mul_f32 v[110:111], v[110:111], v[64:65] op_sel_hi:[1,0]
	v_pk_mul_f32 v[108:109], v[108:109], v[64:65] op_sel_hi:[1,0]
	v_pk_mul_f32 v[106:107], v[106:107], v[64:65] op_sel_hi:[1,0]
	v_pk_mul_f32 v[104:105], v[104:105], v[64:65] op_sel_hi:[1,0]
	v_pk_mul_f32 v[102:103], v[102:103], v[64:65] op_sel_hi:[1,0]
	v_pk_mul_f32 v[100:101], v[100:101], v[64:65] op_sel_hi:[1,0]
	v_pk_mul_f32 v[98:99], v[98:99], v[64:65] op_sel_hi:[1,0]
	v_pk_mul_f32 v[96:97], v[96:97], v[64:65] op_sel_hi:[1,0]
	v_pk_mul_f32 v[94:95], v[94:95], v[64:65] op_sel_hi:[1,0]
	v_pk_mul_f32 v[92:93], v[92:93], v[64:65] op_sel_hi:[1,0]
	v_pk_mul_f32 v[90:91], v[90:91], v[64:65] op_sel_hi:[1,0]
	v_pk_mul_f32 v[88:89], v[88:89], v[64:65] op_sel_hi:[1,0]
	v_pk_mul_f32 v[86:87], v[86:87], v[64:65] op_sel_hi:[1,0]
	v_pk_mul_f32 v[84:85], v[84:85], v[64:65] op_sel_hi:[1,0]
	v_pk_mul_f32 v[82:83], v[82:83], v[64:65] op_sel_hi:[1,0]
	v_pk_mul_f32 v[80:81], v[80:81], v[64:65] op_sel_hi:[1,0]
	v_pk_mul_f32 v[78:79], v[78:79], v[64:65] op_sel_hi:[1,0]
	v_pk_mul_f32 v[76:77], v[76:77], v[64:65] op_sel_hi:[1,0]
	v_pk_mul_f32 v[74:75], v[74:75], v[64:65] op_sel_hi:[1,0]
	v_pk_mul_f32 v[72:73], v[72:73], v[64:65] op_sel_hi:[1,0]
	v_pk_mul_f32 v[70:71], v[70:71], v[64:65] op_sel_hi:[1,0]
	v_pk_mul_f32 v[68:69], v[68:69], v[64:65] op_sel_hi:[1,0]
	v_pk_mul_f32 v[66:67], v[66:67], v[64:65] op_sel_hi:[1,0]

; #define LAS __attribute__((address_space(3)))
; __device__ __forceinline__ f32x16 mfma32(bf16x8 a, bf16x8 b, f32x16 c) { return __builtin_amdgcn_mfma_f32_32x32x16_bf16(a, b, c, 0, 0, 0); }
; template <int MODE> ...
;     ...
;     { const LAS unsigned char* kp = lds + NSA_KB + bufn * 16384 + lane * 16;
; #pragma unroll
;       for (int kt = 0; kt < 2; ++kt) { sn[kt] = zero16();
; #pragma unroll
;           for (int ks = 0; ks < 8; ++ks) sn[kt] = mfma32(*(const LAS bf16x8*)(kp + kt * 8192 + ks * 1024), qf[ks], sn[kt]); } }
;     if (MODE == 1) {
; #pragma unroll
;         for (int kt = 0; kt < 2; ++kt)
; #pragma unroll
;             for (int r = 0; r < 16; ++r) s[kt][r] = (s[kt][r] > -1e29f) ? __builtin_amdgcn_exp2f(s[kt][r] - m_fin) * invl : 0.f;
;         LAS float* impa = (LAS float*)(lds + NSA_IMPA) + w * 8 * 66;
;         LAS float* impb = (LAS float*)(lds + NSA_IMPB) + w * 8 * 66;
; #pragma unroll
;         for (int kt = 0; kt < 2; ++kt)
; #pragma unroll
;             for (int q = 0; q < 4; ++q) {
;                 float A_ = s[kt][4 * q] + s[kt][4 * q + 1] + s[kt][4 * q + 2] + 0.5f * s[kt][4 * q + 3], B_ = 0.5f * s[kt][4 * q + 3];
;                 A_ += __shfl_xor(A_, 1); A_ += __shfl_xor(A_, 2); B_ += __shfl_xor(B_, 1); B_ += __shfl_xor(B_, 2);
;                 const int j = 8 * (2 * idx + kt) + 2 * q + hi;
;                 if (hd == 0) { impa[tl * 66 + j] = A_; impb[tl * 66 + j + 1] = B_; }
;             }
;     } else {
;         float tm = -3.0e38f;
; #pragma unroll
;         for (int kt = 0; kt < 2; ++kt)
; #pragma unroll
;             for (int r = 0; r < 16; r += 2) tm = fmaxf(fmaxf(tm, s[kt][r]), s[kt][r + 1]);
;         tm = tm * cs + offl;
;         tm = max_xor32(tm);
;         const float mn = fmaxf(mrun, tm), al = __builtin_amdgcn_exp2f(mrun - mn); float ps = 0.f;
;         const float om = offl - mn;
; #pragma unroll
;         for (int kt = 0; kt < 2; ++kt)
; #pragma unroll
;             for (int r = 0; r < 16; ++r) { const float p = __builtin_amdgcn_exp2f(s[kt][r] * cs + om); s[kt][r] = p; ps += p; }
;         lrun = lrun * al + ps; mrun = mn;
;         if (MODE != 0) {
;             if (__builtin_amdgcn_ballot_w64(al != 1.0f)) {
; #pragma unroll
;                 for (int dt = 0; dt < 4; ++dt) O[dt] = O[dt] * al;
;             }
;         }
.LBB0_1237:
	s_or_b64 exec, exec, s[10:11]
	s_lshl_b32 s0, s14, 14
	s_add_i32 s0, s0, 0
	v_lshlrev_b32_e32 v170, 4, v32
	v_add_u32_e32 v64, s0, v170
	ds_read_b128 v[218:221], v64
	ds_read_b128 v[224:227], v64 offset:1024
	ds_read_b128 v[228:231], v64 offset:2048
	ds_read_b128 v[232:235], v64 offset:3072
	ds_read_b128 v[236:239], v64 offset:4096
	ds_read_b128 v[240:243], v64 offset:5120
	ds_read_b128 v[244:247], v64 offset:6144
	ds_read_b128 v[248:251], v64 offset:7168
	ds_read_b128 v[172:175], v64 offset:8192
	ds_read_b128 v[176:179], v64 offset:9216
	ds_read_b128 v[180:183], v64 offset:10240
	ds_read_b128 v[184:187], v64 offset:11264
	s_waitcnt lgkmcnt(11)
	v_mfma_f32_32x32x16_bf16 v[32:47], v[218:221], v[154:157], 0
	s_waitcnt lgkmcnt(10)
	v_mfma_f32_32x32x16_bf16 v[32:47], v[224:227], v[130:133], v[32:47]
	ds_read_b128 v[218:221], v64 offset:12288
	ds_read_b128 v[224:227], v64 offset:13312
	s_waitcnt lgkmcnt(11)
	v_mfma_f32_32x32x16_bf16 v[32:47], v[228:231], v[134:137], v[32:47]
	s_waitcnt lgkmcnt(10)
	v_mfma_f32_32x32x16_bf16 v[32:47], v[232:235], v[138:141], v[32:47]
	ds_read_b128 v[228:231], v64 offset:14336
	ds_read_b128 v[232:235], v64 offset:15360
	s_waitcnt lgkmcnt(11)
	v_mfma_f32_32x32x16_bf16 v[32:47], v[236:239], v[142:145], v[32:47]
	s_waitcnt lgkmcnt(10)
	v_mfma_f32_32x32x16_bf16 v[32:47], v[240:243], v[146:149], v[32:47]
	s_waitcnt lgkmcnt(9)
	v_mfma_f32_32x32x16_bf16 v[32:47], v[244:247], v[150:153], v[32:47]
	s_waitcnt lgkmcnt(8)
	v_mfma_f32_32x32x16_bf16 v[32:47], v[248:251], v[158:161], v[32:47]
	s_waitcnt lgkmcnt(7)
	v_mfma_f32_32x32x16_bf16 v[48:63], v[172:175], v[154:157], 0
	s_waitcnt lgkmcnt(6)
	v_mfma_f32_32x32x16_bf16 v[48:63], v[176:179], v[130:133], v[48:63]
	s_waitcnt lgkmcnt(5)
	v_mfma_f32_32x32x16_bf16 v[48:63], v[180:183], v[134:137], v[48:63]
	s_waitcnt lgkmcnt(4)
	v_mfma_f32_32x32x16_bf16 v[48:63], v[184:187], v[138:141], v[48:63]
	v_max3_f32 v64, v0, s78, v1
	v_max3_f32 v64, v64, v2, v3
	v_max3_f32 v64, v64, v4, v5
	v_max3_f32 v64, v64, v6, v7
	v_max3_f32 v64, v64, v8, v9
	v_max3_f32 v64, v64, v10, v11
	s_waitcnt lgkmcnt(3)
	v_mfma_f32_32x32x16_bf16 v[48:63], v[218:221], v[142:145], v[48:63]
	v_max3_f32 v64, v64, v12, v13
	v_max3_f32 v64, v64, v14, v15
	v_max3_f32 v64, v64, v16, v17
	v_max3_f32 v64, v64, v18, v19
	v_max3_f32 v64, v64, v20, v21
	v_max3_f32 v64, v64, v22, v23
	v_max3_f32 v64, v64, v24, v25
	s_waitcnt lgkmcnt(2)
	v_mfma_f32_32x32x16_bf16 v[48:63], v[224:227], v[146:149], v[48:63]
	v_max3_f32 v64, v64, v26, v27
	v_max3_f32 v64, v64, v28, v29
	v_max3_f32 v64, v64, v30, v31
	v_fma_f32 v64, v166, v64, v171
	v_mov_b32_e32 v167, v64
	s_nop 1
	v_permlane32_swap_b32 v64, v167
	s_nop 1
	s_waitcnt lgkmcnt(1)
	v_mfma_f32_32x32x16_bf16 v[48:63], v[228:231], v[150:153], v[48:63]
	v_max_f32_e32 v167, v64, v167
	v_add_f32_e32 v64, 0x41000000, v169
	v_cmp_gt_f32_e32 vcc, v167, v64
	s_nop 1
	v_cndmask_b32_e32 v167, v169, v167, vcc
	v_sub_f32_e32 v64, v169, v167
	v_exp_f32_e32 v64, v64
	s_nop 0
	v_cmp_neq_f32_e32 vcc, 1.0, v64
	s_waitcnt lgkmcnt(0)
	v_mfma_f32_32x32x16_bf16 v[48:63], v[232:235], v[158:161], v[48:63]
	s_cbranch_vccz .LBB0_1228
	v_pk_mul_f32 v[128:129], v[128:129], v[64:65] op_sel_hi:[1,0]
	v_pk_mul_f32 v[126:127], v[126:127], v[64:65] op_sel_hi:[1,0]
	v_pk_mul_f32 v[124:125], v[124:125], v[64:65] op_sel_hi:[1,0]
	v_pk_mul_f32 v[122:123], v[122:123], v[64:65] op_sel_hi:[1,0]
	v_pk_mul_f32 v[120:121], v[120:121], v[64:65] op_sel_hi:[1,0]
	v_pk_mul_f32 v[118:119], v[118:119], v[64:65] op_sel_hi:[1,0]
	v_pk_mul_f32 v[116:117], v[116:117], v[64:65] op_sel_hi:[1,0]
	v_pk_mul_f32 v[114:115], v[114:115], v[64:65] op_sel_hi:[1,0]
	v_pk_mul_f32 v[112:113], v[112:113], v[64:65] op_sel_hi:[1,0]
	v_pk_mul_f32 v[110:111], v[110:111], v[64:65] op_sel_hi:[1,0]
	v_pk_mul_f32 v[108:109], v[108:109], v[64:65] op_sel_hi:[1,0]
	v_pk_mul_f32 v[106:107], v[106:107], v[64:65] op_sel_hi:[1,0]
	v_pk_mul_f32 v[104:105], v[104:105], v[64:65] op_sel_hi:[1,0]
	v_pk_mul_f32 v[102:103], v[102:103], v[64:65] op_sel_hi:[1,0]
	v_pk_mul_f32 v[100:101], v[100:101], v[64:65] op_sel_hi:[1,0]
	v_pk_mul_f32 v[98:99], v[98:99], v[64:65] op_sel_hi:[1,0]
	v_pk_mul_f32 v[96:97], v[96:97], v[64:65] op_sel_hi:[1,0]
	v_pk_mul_f32 v[94:95], v[94:95], v[64:65] op_sel_hi:[1,0]
	v_pk_mul_f32 v[92:93], v[92:93], v[64:65] op_sel_hi:[1,0]
	v_pk_mul_f32 v[90:91], v[90:91], v[64:65] op_sel_hi:[1,0]
	v_pk_mul_f32 v[88:89], v[88:89], v[64:65] op_sel_hi:[1,0]
	v_pk_mul_f32 v[86:87], v[86:87], v[64:65] op_sel_hi:[1,0]
	v_pk_mul_f32 v[84:85], v[84:85], v[64:65] op_sel_hi:[1,0]
	v_pk_mul_f32 v[82:83], v[82:83], v[64:65] op_sel_hi:[1,0]
	v_pk_mul_f32 v[80:81], v[80:81], v[64:65] op_sel_hi:[1,0]
	v_pk_mul_f32 v[78:79], v[78:79], v[64:65] op_sel_hi:[1,0]
	v_pk_mul_f32 v[76:77], v[76:77], v[64:65] op_sel_hi:[1,0]
	v_pk_mul_f32 v[74:75], v[74:75], v[64:65] op_sel_hi:[1,0]
	v_pk_mul_f32 v[72:73], v[72:73], v[64:65] op_sel_hi:[1,0]
	v_pk_mul_f32 v[70:71], v[70:71], v[64:65] op_sel_hi:[1,0]
	v_pk_mul_f32 v[68:69], v[68:69], v[64:65] op_sel_hi:[1,0]
	v_pk_mul_f32 v[66:67], v[66:67], v[64:65] op_sel_hi:[1,0]
	s_branch .LBB0_1228
